# LRU unit: gate-tile LDS write deferred to just before the gate-pass barrier so its load latency overlaps the gate arithmetic
# speedup vs baseline: 1.0073x; 1.0009x over previous
.LBB0_737:
	s_lshl_b32 s68, s78, 6
	v_lshl_add_u64 v[30:31], v[22:23], 0, s[68:69]
	v_lshl_add_u64 v[34:35], v[24:25], 0, s[68:69]
	global_load_dwordx4 v[210:213], v[30:31], off offset:1024 nt
	s_nop 0
	global_load_dwordx4 v[214:217], v[34:35], off offset:1024 nt
	s_lshl_b32 s53, s78, 5
	v_or_b32_e32 v0, s53, v109
	v_readlane_b32 s4, v254, 16
	v_lshlrev_b32_e32 v38, 1, v0
	v_add3_u32 v38, 0, v38, v110
	v_lshl_add_u32 v152, v0, 2, s4
	v_or_b32_e32 v153, 16, v0
	v_lshl_add_u32 v39, v153, 2, s4
	s_or_b32 s68, s53, s92
	v_mov_b32_e32 v151, 0
	s_xor_b64 s[94:95], s[26:27], -1
	v_add_u32_e32 v170, s68, v121
	v_add_u32_e32 v171, s68, v122
	v_add_u32_e32 v172, s68, v123
	v_mov_b32_e32 v150, 0
	v_mov_b32_e32 v149, 0
	v_mov_b32_e32 v148, 0
	v_mov_b32_e32 v147, 0
	v_mov_b32_e32 v146, 0
	v_mov_b32_e32 v145, 0
	v_mov_b32_e32 v144, 0
	v_mov_b32_e32 v143, 0
	v_mov_b32_e32 v142, 0
	v_mov_b32_e32 v141, 0
	v_mov_b32_e32 v140, 0
	v_mov_b32_e32 v139, 0
	v_mov_b32_e32 v138, 0
	v_mov_b32_e32 v137, 0
	v_mov_b32_e32 v136, 0
	s_mov_b64 s[96:97], -1
	s_mov_b32 s7, 0
	ds_read2st64_b32 v[30:31], v152 offset1:1
	ds_read2st64_b32 v[32:33], v152 offset0:2 offset1:3
	ds_read_b32 v154, v152 offset:1024
	ds_read_u16 v34, v38
	ds_read_u16 v35, v38 offset:32
	ds_read_u16 v36, v38 offset:144
	ds_read_u16 v37, v38 offset:288
	ds_read_u16 v40, v38 offset:432
	ds_read_u16 v41, v38 offset:576
	ds_read_u16 v42, v38 offset:464
	ds_read_u16 v43, v38 offset:320
	ds_read_u16 v44, v38 offset:176
	ds_read_u16 v45, v38 offset:720
	ds_read_u16 v46, v38 offset:864
	ds_read_u16 v47, v38 offset:2304
	ds_read_u16 v48, v38 offset:2448
	ds_read_u16 v49, v38 offset:2336
	ds_read_u16 v50, v38 offset:896
	ds_read_u16 v51, v38 offset:752
	ds_read_u16 v52, v38 offset:608
	ds_read_u16 v53, v38 offset:2592
	ds_read_u16 v54, v38 offset:2736
	ds_read_u16 v55, v38 offset:2880
	ds_read_u16 v56, v38 offset:3024
	ds_read_u16 v57, v38 offset:2912
	ds_read_u16 v58, v38 offset:2768
	ds_read_u16 v59, v38 offset:2624
	ds_read_u16 v60, v38 offset:2480
	ds_read_u16 v61, v38 offset:3168
	ds_read_u16 v62, v38 offset:3200
	ds_read_u16 v38, v38 offset:3056
	s_waitcnt lgkmcnt(14)
	v_lshlrev_b32_e32 v34, 16, v34
	v_lshlrev_b32_e32 v36, 16, v36
	v_lshlrev_b32_e32 v37, 16, v37
	v_lshlrev_b32_e32 v40, 16, v40
	v_lshlrev_b32_e32 v47, 16, v47
	v_lshlrev_b32_e32 v48, 16, v48
	s_waitcnt lgkmcnt(10)
	v_lshlrev_b32_e32 v53, 16, v53
	s_waitcnt lgkmcnt(9)
	v_lshlrev_b32_e32 v54, 16, v54
	v_lshlrev_b32_e32 v41, 16, v41
	s_waitcnt lgkmcnt(8)
	v_lshlrev_b32_e32 v55, 16, v55
	v_fma_f32 v155, v30, v34, v154
	v_fma_f32 v156, v30, v36, v154
	v_fma_f32 v157, v30, v37, v154
	v_fma_f32 v158, v30, v40, v154
	v_fma_f32 v159, v30, v47, v154
	v_fma_f32 v160, v30, v48, v154
	v_fma_f32 v161, v30, v53, v154
	v_fmac_f32_e32 v154, v30, v54
	v_lshlrev_b32_e32 v45, 16, v45
	s_waitcnt lgkmcnt(7)
	v_lshlrev_b32_e32 v56, 16, v56
	v_fmac_f32_e32 v155, v31, v36
	v_fmac_f32_e32 v156, v31, v37
	v_fmac_f32_e32 v157, v31, v40
	v_fmac_f32_e32 v158, v31, v41
	v_fmac_f32_e32 v159, v31, v48
	v_fmac_f32_e32 v160, v31, v53
	v_fmac_f32_e32 v161, v31, v54
	v_fmac_f32_e32 v154, v31, v55
	v_lshlrev_b32_e32 v46, 16, v46
	s_waitcnt lgkmcnt(2)
	v_lshlrev_b32_e32 v61, 16, v61
	v_fmac_f32_e32 v155, v32, v37
	v_fmac_f32_e32 v156, v32, v40
	v_fmac_f32_e32 v157, v32, v41
	v_fmac_f32_e32 v158, v32, v45
	v_fmac_f32_e32 v159, v32, v53
	v_fmac_f32_e32 v160, v32, v54
	v_fmac_f32_e32 v161, v32, v55
	v_fmac_f32_e32 v154, v32, v56
	v_fmac_f32_e32 v155, v33, v40
	v_fmac_f32_e32 v156, v33, v41
	v_fmac_f32_e32 v157, v33, v45
	v_fmac_f32_e32 v158, v33, v46
	v_fmac_f32_e32 v159, v33, v54
	v_fmac_f32_e32 v160, v33, v55
	v_fmac_f32_e32 v161, v33, v56
	v_fmac_f32_e32 v154, v33, v61
	ds_read2st64_b32 v[30:31], v39 offset1:1
	ds_read2st64_b32 v[32:33], v39 offset0:2 offset1:3
	ds_read_b32 v162, v39 offset:1024
	v_lshlrev_b32_e32 v34, 16, v35
	v_lshlrev_b32_e32 v35, 16, v44
	v_lshlrev_b32_e32 v36, 16, v43
	v_lshlrev_b32_e32 v37, 16, v42
	s_waitcnt lgkmcnt(0)
	v_fma_f32 v163, v30, v34, v162
	v_fmac_f32_e32 v163, v31, v35
	v_fma_f32 v164, v30, v35, v162
	v_fmac_f32_e32 v163, v32, v36
	v_fmac_f32_e32 v164, v31, v36
	v_fma_f32 v165, v30, v36, v162
	v_lshlrev_b32_e32 v39, 16, v52
	v_fmac_f32_e32 v163, v33, v37
	v_fmac_f32_e32 v164, v32, v37
	v_fmac_f32_e32 v165, v31, v37
	v_fma_f32 v166, v30, v37, v162
	v_lshlrev_b32_e32 v34, 16, v49
	v_lshlrev_b32_e32 v35, 16, v60
	v_lshlrev_b32_e32 v36, 16, v59
	v_lshlrev_b32_e32 v37, 16, v58
	v_fmac_f32_e32 v164, v33, v39
	v_fmac_f32_e32 v165, v32, v39
	v_fmac_f32_e32 v166, v31, v39
	v_lshlrev_b32_e32 v39, 16, v57
	v_fma_f32 v167, v30, v34, v162
	v_fma_f32 v168, v30, v35, v162
	v_fma_f32 v169, v30, v36, v162
	v_fmac_f32_e32 v162, v30, v37
	v_lshlrev_b32_e32 v40, 16, v51
	v_lshlrev_b32_e32 v38, 16, v38
	v_fmac_f32_e32 v167, v31, v35
	v_fmac_f32_e32 v168, v31, v36
	v_fmac_f32_e32 v169, v31, v37
	v_fmac_f32_e32 v162, v31, v39
	v_lshlrev_b32_e32 v41, 16, v50
	v_fmac_f32_e32 v165, v33, v40
	v_fmac_f32_e32 v166, v32, v40
	v_lshlrev_b32_e32 v40, 16, v62
	v_fmac_f32_e32 v167, v32, v36
	v_fmac_f32_e32 v168, v32, v37
	v_fmac_f32_e32 v169, v32, v39
	v_fmac_f32_e32 v162, v32, v38
	v_add_u32_e32 v46, s68, v18
	v_fmac_f32_e32 v166, v33, v41
	v_fmac_f32_e32 v167, v33, v37
	v_fmac_f32_e32 v168, v33, v39
	v_fmac_f32_e32 v169, v33, v38
	v_fmac_f32_e32 v162, v33, v40
	v_ashrrev_i32_e32 v47, 31, v46
	v_lshl_add_u64 v[48:49], s[68:69], 0, v[18:19]
	v_mov_b32_e32 v44, 0
	v_mov_b32_e32 v45, v151
	v_mov_b32_e32 v42, 0
	v_mov_b32_e32 v43, v151
	v_mov_b32_e32 v40, 0
	v_mov_b32_e32 v41, v151
	v_mov_b32_e32 v38, 0
	v_mov_b32_e32 v39, v151
	v_mov_b32_e32 v36, 0
	v_mov_b32_e32 v37, v151
	v_mov_b32_e32 v34, 0
	v_mov_b32_e32 v35, v151
	v_mov_b32_e32 v32, 0
	v_mov_b32_e32 v33, v151
	v_mov_b32_e32 v30, 0
	v_mov_b32_e32 v31, v151
.LBB0_738:
	s_lshl_b32 s68, s7, 7
	v_or_b32_e32 v50, s68, v0
	v_mad_u32_u24 v51, v50, s55, v111
	v_lshl_add_u32 v51, v51, 1, s52
	ds_read_b128 v[56:59], v51
	ds_read_b128 v[60:63], v51 offset:64
	v_mad_u32_u24 v50, v50, s55, v112
	v_lshl_add_u32 v54, v50, 1, s52
	ds_read_b128 v[64:67], v54
	ds_read_b128 v[68:71], v54 offset:64
	s_waitcnt lgkmcnt(0)
	v_mfma_f32_16x16x32_bf16 v[50:53], v[2:5], v[56:59], 0
	v_lshl_add_u32 v54, s7, 8, v152
	s_and_b64 s[4:5], s[96:97], exec
	v_add_u32_e32 v55, 0x400, v54
	s_waitcnt lgkmcnt(2)
	v_mfma_f32_16x16x32_bf16 v[84:87], v[6:9], v[60:63], v[50:53]
	s_cselect_b32 s79, 0, 3
	ds_read2_b32 v[76:77], v55 offset0:64 offset1:80
	s_cmp_eq_u32 s79, 1
	v_add_u32_e32 v50, 0x800, v54
	s_cselect_b64 vcc, -1, 0
	s_cmp_eq_u32 s79, 2
	s_waitcnt lgkmcnt(2)
	v_mfma_f32_16x16x32_bf16 v[78:81], v[2:5], v[64:67], 0
	ds_read2_b32 v[72:73], v50 offset0:64 offset1:80
	v_cndmask_b32_e32 v50, v84, v85, vcc
	s_cselect_b64 s[26:27], -1, 0
	s_cmp_eq_u32 s79, 3
	v_cndmask_b32_e64 v50, v50, v86, s[26:27]
	s_cselect_b64 s[28:29], -1, 0
	v_cndmask_b32_e64 v50, v50, v87, s[28:29]
	s_waitcnt lgkmcnt(0)
	v_add_f32_e32 v50, v76, v50
	v_mfma_f32_16x16x32_bf16 v[88:91], v[6:9], v[68:71], v[78:81]
	v_mul_f32_e32 v50, 0xbfb8aa3b, v50
	v_exp_f32_e32 v50, v50
	ds_read2_b32 v[74:75], v55 offset0:192 offset1:208
	s_and_b64 s[4:5], s[96:97], exec
	s_cselect_b32 s4, 1, 2
	s_nop 2
	v_cndmask_b32_e32 v51, v88, v89, vcc
	v_cndmask_b32_e64 v51, v51, v90, s[26:27]
	v_add_f32_e32 v50, 1.0, v50
	v_cndmask_b32_e64 v51, v51, v91, s[28:29]
	v_rcp_f32_e32 v50, v50
	s_waitcnt lgkmcnt(0)
	v_add_f32_e32 v51, v74, v51
	v_mul_f32_e32 v51, 0xbfb8aa3b, v51
	v_exp_f32_e32 v51, v51
	v_mul_f32_e32 v50, 0xc1000000, v50
	v_mul_f32_e32 v50, v72, v50
	v_mul_f32_e32 v50, 0x3fb8aa3b, v50
	v_exp_f32_e32 v173, v50
	v_add_f32_e32 v50, 1.0, v51
	v_rcp_f32_e32 v50, v50
	s_cmp_eq_u32 s4, 1
	v_cndmask_b32_e64 v51, v158, v155, s[96:97]
	s_cselect_b64 s[30:31], -1, 0
	s_cmp_eq_u32 s4, 2
	v_mul_f32_e32 v81, v51, v50
	v_cndmask_b32_e64 v50, v84, v85, s[30:31]
	s_cselect_b64 s[34:35], -1, 0
	s_cmp_eq_u32 s4, 3
	v_cndmask_b32_e64 v50, v50, v86, s[34:35]
	s_cselect_b64 s[36:37], -1, 0
	v_cndmask_b32_e64 v50, v50, v87, s[36:37]
	v_add_f32_e32 v50, v76, v50
	v_mul_f32_e32 v50, 0xbfb8aa3b, v50
	v_exp_f32_e32 v50, v50
	v_cndmask_b32_e64 v51, v88, v89, s[30:31]
	v_cndmask_b32_e64 v51, v51, v90, s[34:35]
	v_cndmask_b32_e64 v51, v51, v91, s[36:37]
	v_add_f32_e32 v50, 1.0, v50
	v_rcp_f32_e32 v50, v50
	v_add_f32_e32 v51, v74, v51
	v_fma_f32 v52, -v173, v173, 1.0
	v_mul_f32_e32 v51, 0xbfb8aa3b, v51
	v_sqrt_f32_e32 v79, v52
	v_exp_f32_e32 v52, v51
	s_and_b64 s[38:39], s[96:97], exec
	v_mul_f32_e32 v50, 0xc1000000, v50
	s_cselect_b32 s5, 2, 1
	v_mul_f32_e32 v50, v72, v50
	s_cmp_eq_u32 s5, 1
	v_mul_f32_e32 v50, 0x3fb8aa3b, v50
	s_cselect_b64 s[38:39], -1, 0
	s_cmp_eq_u32 s5, 2
	v_exp_f32_e32 v51, v50
	v_add_f32_e32 v50, 1.0, v52
	v_cndmask_b32_e64 v52, v84, v85, s[38:39]
	s_cselect_b64 s[40:41], -1, 0
	s_cmp_eq_u32 s5, 3
	v_cndmask_b32_e64 v52, v52, v86, s[40:41]
	s_cselect_b64 s[42:43], -1, 0
	v_cndmask_b32_e64 v52, v52, v87, s[42:43]
	v_add_f32_e32 v52, v76, v52
	v_mul_f32_e32 v52, 0xbfb8aa3b, v52
	v_exp_f32_e32 v52, v52
	v_cndmask_b32_e64 v53, v88, v89, s[38:39]
	v_cndmask_b32_e64 v53, v53, v90, s[40:41]
	v_cndmask_b32_e64 v53, v53, v91, s[42:43]
	v_add_f32_e32 v52, 1.0, v52
	v_rcp_f32_e32 v52, v52
	v_add_f32_e32 v53, v74, v53
	v_mul_f32_e32 v53, 0xbfb8aa3b, v53
	v_exp_f32_e32 v53, v53
	v_mul_f32_e32 v52, 0xc1000000, v52
	v_mul_f32_e32 v52, v72, v52
	v_mul_f32_e32 v52, 0x3fb8aa3b, v52
	v_exp_f32_e32 v55, v52
	v_add_f32_e32 v52, 1.0, v53
	v_rcp_f32_e32 v52, v52
	s_and_b64 s[44:45], s[96:97], exec
	s_cselect_b32 s6, 3, 0
	s_cmp_eq_u32 s6, 1
	v_cndmask_b32_e64 v53, v156, v157, s[96:97]
	s_cselect_b64 s[44:45], -1, 0
	s_cmp_eq_u32 s6, 2
	v_mul_f32_e32 v82, v53, v52
	v_cndmask_b32_e64 v52, v84, v85, s[44:45]
	s_cselect_b64 s[46:47], -1, 0
	s_cmp_eq_u32 s6, 3
	v_cndmask_b32_e64 v52, v52, v86, s[46:47]
	s_cselect_b64 s[48:49], -1, 0
	v_cndmask_b32_e64 v52, v52, v87, s[48:49]
	v_add_f32_e32 v52, v76, v52
	v_mul_f32_e32 v52, 0xbfb8aa3b, v52
	v_exp_f32_e32 v52, v52
	v_cndmask_b32_e64 v83, v88, v89, s[44:45]
	v_cndmask_b32_e64 v83, v83, v90, s[46:47]
	v_cndmask_b32_e64 v83, v83, v91, s[48:49]
	v_add_f32_e32 v52, 1.0, v52
	v_rcp_f32_e32 v52, v52
	v_add_f32_e32 v83, v74, v83
	v_mul_f32_e32 v83, 0xbfb8aa3b, v83
	v_exp_f32_e32 v83, v83
	v_mfma_f32_16x16x32_bf16 v[84:87], v[10:13], v[56:59], 0
	v_mul_f32_e32 v52, 0xc1000000, v52
	v_mul_f32_e32 v52, v72, v52
	v_mul_f32_e32 v52, 0x3fb8aa3b, v52
	v_exp_f32_e32 v59, v52
	v_add_f32_e32 v52, 1.0, v83
	v_rcp_f32_e32 v52, v52
	v_mfma_f32_16x16x32_bf16 v[60:63], v[14:17], v[60:63], v[84:87]
	v_cndmask_b32_e64 v53, v155, v158, s[96:97]
	v_fma_f32 v56, -v59, v59, 1.0
	v_mul_f32_e32 v88, v53, v52
	v_mfma_f32_16x16x32_bf16 v[64:67], v[10:13], v[64:67], 0
	v_sqrt_f32_e32 v58, v56
	s_nop 2
	v_cndmask_b32_e32 v52, v60, v61, vcc
	v_cndmask_b32_e64 v52, v52, v62, s[26:27]
	v_cndmask_b32_e64 v52, v52, v63, s[28:29]
	v_add_f32_e32 v52, v76, v52
	v_mfma_f32_16x16x32_bf16 v[64:67], v[14:17], v[68:71], v[64:67]
	v_mul_f32_e32 v52, 0xbfb8aa3b, v52
	v_exp_f32_e32 v52, v52
	v_cndmask_b32_e64 v69, v160, v161, s[96:97]
	v_cndmask_b32_e64 v70, v159, v154, s[96:97]
	v_cndmask_b32_e64 v83, v168, v169, s[96:97]
	s_nop 2
	v_cndmask_b32_e32 v53, v64, v65, vcc
	v_cndmask_b32_e64 v53, v53, v66, s[26:27]
	v_add_f32_e32 v52, 1.0, v52
	v_cndmask_b32_e64 v53, v53, v67, s[28:29]
	v_rcp_f32_e32 v52, v52
	v_add_f32_e32 v53, v74, v53
	v_mul_f32_e32 v53, 0xbfb8aa3b, v53
	v_exp_f32_e32 v53, v53
	v_mul_f32_e32 v52, 0xc1000000, v52
	v_mul_f32_e32 v52, v72, v52
	v_mul_f32_e32 v52, 0x3fb8aa3b, v52
	v_exp_f32_e32 v174, v52
	v_add_f32_e32 v52, 1.0, v53
	v_rcp_f32_e32 v52, v52
	v_cndmask_b32_e64 v53, v154, v159, s[96:97]
	v_fma_f32 v56, -v174, v174, 1.0
	v_sqrt_f32_e32 v85, v56
	v_mul_f32_e32 v87, v53, v52
	v_cndmask_b32_e64 v52, v60, v61, s[30:31]
	v_cndmask_b32_e64 v52, v52, v62, s[34:35]
	v_cndmask_b32_e64 v52, v52, v63, s[36:37]
	v_add_f32_e32 v52, v76, v52
	v_mul_f32_e32 v52, 0xbfb8aa3b, v52
	v_exp_f32_e32 v52, v52
	v_cndmask_b32_e64 v53, v64, v65, s[30:31]
	v_cndmask_b32_e64 v53, v53, v66, s[34:35]
	v_cndmask_b32_e64 v53, v53, v67, s[36:37]
	v_add_f32_e32 v52, 1.0, v52
	v_rcp_f32_e32 v52, v52
	v_add_f32_e32 v53, v74, v53
	v_mul_f32_e32 v53, 0xbfb8aa3b, v53
	v_exp_f32_e32 v56, v53
	v_mul_f32_e32 v52, 0xc1000000, v52
	v_mul_f32_e32 v52, v72, v52
	v_mul_f32_e32 v52, 0x3fb8aa3b, v52
	v_exp_f32_e32 v53, v52
	v_add_f32_e32 v52, 1.0, v56
	v_cndmask_b32_e64 v56, v60, v61, s[38:39]
	v_cndmask_b32_e64 v56, v56, v62, s[40:41]
	v_cndmask_b32_e64 v56, v56, v63, s[42:43]
	v_add_f32_e32 v56, v76, v56
	v_mul_f32_e32 v56, 0xbfb8aa3b, v56
	v_exp_f32_e32 v56, v56
	v_cndmask_b32_e64 v57, v64, v65, s[38:39]
	v_cndmask_b32_e64 v57, v57, v66, s[40:41]
	v_cndmask_b32_e64 v57, v57, v67, s[42:43]
	v_add_f32_e32 v56, 1.0, v56
	v_rcp_f32_e32 v56, v56
	v_add_f32_e32 v57, v74, v57
	v_mul_f32_e32 v57, 0xbfb8aa3b, v57
	v_exp_f32_e32 v68, v57
	v_mul_f32_e32 v56, 0xc1000000, v56
	v_cndmask_b32_e64 v60, v60, v61, s[44:45]
	v_cndmask_b32_e64 v61, v64, v65, s[44:45]
	v_mul_f32_e32 v56, v72, v56
	v_cndmask_b32_e64 v61, v61, v66, s[46:47]
	v_mul_f32_e32 v56, 0x3fb8aa3b, v56
	v_cndmask_b32_e64 v61, v61, v67, s[48:49]
	v_exp_f32_e32 v57, v56
	v_add_f32_e32 v56, 1.0, v68
	v_add_f32_e32 v61, v74, v61
	v_rcp_f32_e32 v68, v56
	v_mul_f32_e32 v61, 0xbfb8aa3b, v61
	v_exp_f32_e32 v71, v61
	v_or_b32_e32 v61, s68, v153
	v_cndmask_b32_e64 v60, v60, v62, s[46:47]
	v_mad_u32_u24 v62, v61, s55, v111
	v_lshl_add_u32 v62, v62, 1, s52
	v_mul_f32_e32 v106, v69, v68
	ds_read_b128 v[66:69], v62
	v_mad_u32_u24 v61, v61, s55, v112
	v_lshl_add_u32 v61, v61, 1, s52
	ds_read_b128 v[90:93], v61
	ds_read_b128 v[94:97], v62 offset:64
	v_cndmask_b32_e64 v60, v60, v63, s[48:49]
	s_waitcnt lgkmcnt(0)
	v_mfma_f32_16x16x32_bf16 v[62:65], v[2:5], v[66:69], 0
	ds_read_b128 v[98:101], v61 offset:64
	v_add_f32_e32 v60, v76, v60
	v_mul_f32_e32 v60, 0xbfb8aa3b, v60
	s_waitcnt lgkmcnt(1)
	v_mfma_f32_16x16x32_bf16 v[176:179], v[6:9], v[94:97], v[62:65]
	v_exp_f32_e32 v60, v60
	v_rcp_f32_e32 v78, v50
	v_fma_f32 v50, -v51, v51, 1.0
	v_mfma_f32_16x16x32_bf16 v[102:105], v[2:5], v[90:93], 0
	v_add_f32_e32 v60, 1.0, v60
	s_nop 2
	v_cndmask_b32_e32 v62, v176, v177, vcc
	v_cndmask_b32_e64 v62, v62, v178, s[26:27]
	v_cndmask_b32_e64 v62, v62, v179, s[28:29]
	v_add_f32_e32 v62, v77, v62
	s_waitcnt lgkmcnt(0)
	v_mfma_f32_16x16x32_bf16 v[102:105], v[6:9], v[98:101], v[102:105]
	v_mul_f32_e32 v62, 0xbfb8aa3b, v62
	v_exp_f32_e32 v62, v62
	v_rcp_f32_e32 v60, v60
	v_mfma_f32_16x16x32_bf16 v[90:93], v[10:13], v[90:93], 0
	v_sqrt_f32_e32 v50, v50
	s_nop 2
	v_cndmask_b32_e32 v63, v102, v103, vcc
	v_cndmask_b32_e64 v63, v63, v104, s[26:27]
	v_add_f32_e32 v62, 1.0, v62
	v_cndmask_b32_e64 v63, v63, v105, s[28:29]
	v_rcp_f32_e32 v62, v62
	v_add_f32_e32 v63, v75, v63
	v_mul_f32_e32 v63, 0xbfb8aa3b, v63
	v_exp_f32_e32 v63, v63
	v_mul_f32_e32 v62, 0xc1000000, v62
	v_mul_f32_e32 v62, v73, v62
	v_mul_f32_e32 v62, 0x3fb8aa3b, v62
	v_exp_f32_e32 v175, v62
	v_add_f32_e32 v62, 1.0, v63
	v_rcp_f32_e32 v62, v62
	v_cndmask_b32_e64 v63, v166, v163, s[96:97]
	v_fma_f32 v64, -v175, v175, 1.0
	v_sqrt_f32_e32 v181, v64
	v_mul_f32_e32 v183, v63, v62
	v_cndmask_b32_e64 v62, v176, v177, s[30:31]
	v_cndmask_b32_e64 v62, v62, v178, s[34:35]
	v_cndmask_b32_e64 v62, v62, v179, s[36:37]
	v_add_f32_e32 v62, v77, v62
	v_mul_f32_e32 v62, 0xbfb8aa3b, v62
	v_exp_f32_e32 v62, v62
	v_cndmask_b32_e64 v63, v102, v103, s[30:31]
	v_cndmask_b32_e64 v63, v63, v104, s[34:35]
	v_cndmask_b32_e64 v63, v63, v105, s[36:37]
	v_add_f32_e32 v62, 1.0, v62
	v_rcp_f32_e32 v62, v62
	v_add_f32_e32 v63, v75, v63
	v_mul_f32_e32 v63, 0xbfb8aa3b, v63
	v_exp_f32_e32 v64, v63
	v_mul_f32_e32 v62, 0xc1000000, v62
	v_mul_f32_e32 v62, v73, v62
	v_mul_f32_e32 v62, 0x3fb8aa3b, v62
	v_exp_f32_e32 v63, v62
	v_add_f32_e32 v62, 1.0, v64
	v_cndmask_b32_e64 v64, v176, v177, s[38:39]
	v_cndmask_b32_e64 v64, v64, v178, s[40:41]
	v_cndmask_b32_e64 v64, v64, v179, s[42:43]
	v_add_f32_e32 v64, v77, v64
	v_mul_f32_e32 v64, 0xbfb8aa3b, v64
	v_mul_f32_e32 v60, 0xc1000000, v60
	v_exp_f32_e32 v64, v64
	v_mul_f32_e32 v60, v72, v60
	v_mul_f32_e32 v60, 0x3fb8aa3b, v60
	v_exp_f32_e32 v61, v60
	v_add_f32_e32 v60, 1.0, v71
	v_cndmask_b32_e64 v65, v102, v103, s[38:39]
	v_rcp_f32_e32 v71, v60
	v_cndmask_b32_e64 v65, v65, v104, s[40:41]
	v_add_f32_e32 v64, 1.0, v64
	v_cndmask_b32_e64 v65, v65, v105, s[42:43]
	v_rcp_f32_e32 v64, v64
	v_add_f32_e32 v65, v75, v65
	v_mul_f32_e32 v65, 0xbfb8aa3b, v65
	v_mul_f32_e32 v74, v70, v71
	v_exp_f32_e32 v70, v65
	v_mul_f32_e32 v64, 0xc1000000, v64
	v_mul_f32_e32 v64, v73, v64
	v_mul_f32_e32 v64, 0x3fb8aa3b, v64
	v_exp_f32_e32 v65, v64
	v_add_f32_e32 v64, 1.0, v70
	v_rcp_f32_e32 v70, v64
	v_cndmask_b32_e64 v71, v164, v165, s[96:97]
	v_cndmask_b32_e64 v72, v102, v103, s[44:45]
	v_cndmask_b32_e64 v72, v72, v104, s[46:47]
	v_mul_f32_e32 v76, v71, v70
	v_cndmask_b32_e64 v70, v176, v177, s[44:45]
	v_cndmask_b32_e64 v70, v70, v178, s[46:47]
	v_cndmask_b32_e64 v70, v70, v179, s[48:49]
	v_add_f32_e32 v70, v77, v70
	v_mul_f32_e32 v70, 0xbfb8aa3b, v70
	v_exp_f32_e32 v70, v70
	v_cndmask_b32_e64 v72, v72, v105, s[48:49]
	v_add_f32_e32 v72, v75, v72
	v_mul_f32_e32 v72, 0xbfb8aa3b, v72
	v_add_f32_e32 v70, 1.0, v70
	v_rcp_f32_e32 v70, v70
	v_exp_f32_e32 v72, v72
	v_mfma_f32_16x16x32_bf16 v[102:105], v[10:13], v[66:69], 0
	v_cndmask_b32_e64 v71, v163, v166, s[96:97]
	v_mul_f32_e32 v66, 0xc1000000, v70
	v_mul_f32_e32 v66, v73, v66
	v_mul_f32_e32 v66, 0x3fb8aa3b, v66
	v_exp_f32_e32 v69, v66
	v_add_f32_e32 v66, 1.0, v72
	v_rcp_f32_e32 v66, v66
	v_mfma_f32_16x16x32_bf16 v[94:97], v[14:17], v[94:97], v[102:105]
	v_fma_f32 v67, -v69, v69, 1.0
	v_sqrt_f32_e32 v68, v67
	v_mul_f32_e32 v178, v71, v66
	v_mfma_f32_16x16x32_bf16 v[90:93], v[14:17], v[98:101], v[90:93]
	v_rcp_f32_e32 v180, v62
	s_nop 2
	v_cndmask_b32_e32 v66, v94, v95, vcc
	v_cndmask_b32_e64 v66, v66, v96, s[26:27]
	v_cndmask_b32_e64 v66, v66, v97, s[28:29]
	v_add_f32_e32 v66, v77, v66
	v_mul_f32_e32 v66, 0xbfb8aa3b, v66
	v_exp_f32_e32 v66, v66
	v_cndmask_b32_e32 v67, v90, v91, vcc
	v_cndmask_b32_e64 v67, v67, v92, s[26:27]
	v_cndmask_b32_e64 v67, v67, v93, s[28:29]
	v_add_f32_e32 v66, 1.0, v66
	v_rcp_f32_e32 v66, v66
	v_add_f32_e32 v67, v75, v67
	v_mul_f32_e32 v67, 0xbfb8aa3b, v67
	v_exp_f32_e32 v67, v67
	v_mul_f32_e32 v66, 0xc1000000, v66
	v_mul_f32_e32 v66, v73, v66
	v_mul_f32_e32 v66, 0x3fb8aa3b, v66
	v_exp_f32_e32 v176, v66
	v_add_f32_e32 v66, 1.0, v67
	v_rcp_f32_e32 v66, v66
	v_cndmask_b32_e64 v67, v162, v167, s[96:97]
	v_fma_f32 v70, -v176, v176, 1.0
	v_sqrt_f32_e32 v185, v70
	v_mul_f32_e32 v187, v67, v66
	v_cndmask_b32_e64 v66, v94, v95, s[30:31]
	v_cndmask_b32_e64 v66, v66, v96, s[34:35]
	v_cndmask_b32_e64 v66, v66, v97, s[36:37]
	v_add_f32_e32 v66, v77, v66
	v_mul_f32_e32 v66, 0xbfb8aa3b, v66
	v_exp_f32_e32 v66, v66
	v_cndmask_b32_e64 v67, v90, v91, s[30:31]
	v_cndmask_b32_e64 v67, v67, v92, s[34:35]
	v_cndmask_b32_e64 v67, v67, v93, s[36:37]
	v_add_f32_e32 v66, 1.0, v66
	v_rcp_f32_e32 v66, v66
	v_add_f32_e32 v67, v75, v67
	v_mul_f32_e32 v67, 0xbfb8aa3b, v67
	v_exp_f32_e32 v70, v67
	v_mul_f32_e32 v66, 0xc1000000, v66
	v_mul_f32_e32 v66, v73, v66
	v_mul_f32_e32 v66, 0x3fb8aa3b, v66
	v_exp_f32_e32 v67, v66
	v_add_f32_e32 v66, 1.0, v70
	v_cndmask_b32_e64 v70, v94, v95, s[38:39]
	v_cndmask_b32_e64 v70, v70, v96, s[40:41]
	v_cndmask_b32_e64 v70, v70, v97, s[42:43]
	v_add_f32_e32 v70, v77, v70
	v_mul_f32_e32 v70, 0xbfb8aa3b, v70
	v_exp_f32_e32 v70, v70
	v_cndmask_b32_e64 v71, v90, v91, s[38:39]
	v_cndmask_b32_e64 v71, v71, v92, s[40:41]
	v_cndmask_b32_e64 v71, v71, v93, s[42:43]
	v_add_f32_e32 v70, 1.0, v70
	v_rcp_f32_e32 v70, v70
	v_add_f32_e32 v71, v75, v71
	v_mul_f32_e32 v71, 0xbfb8aa3b, v71
	v_exp_f32_e32 v72, v71
	v_mul_f32_e32 v70, 0xc1000000, v70
	v_mul_f32_e32 v70, v73, v70
	v_mul_f32_e32 v70, 0x3fb8aa3b, v70
	v_exp_f32_e32 v71, v70
	v_add_f32_e32 v70, 1.0, v72
	v_rcp_f32_e32 v72, v70
	v_fma_f32 v62, -v63, v63, 1.0
	v_cndmask_b32_e64 v80, v157, v156, s[96:97]
	v_fma_f32 v54, -v55, v55, 1.0
	v_mul_f32_e32 v188, v83, v72
	v_cndmask_b32_e64 v72, v94, v95, s[44:45]
	v_cndmask_b32_e64 v72, v72, v96, s[46:47]
	v_cndmask_b32_e64 v72, v72, v97, s[48:49]
	v_add_f32_e32 v72, v77, v72
	v_mul_f32_e32 v72, 0xbfb8aa3b, v72
	v_exp_f32_e32 v72, v72
	v_cndmask_b32_e64 v77, v90, v91, s[44:45]
	v_cndmask_b32_e64 v77, v77, v92, s[46:47]
	v_cndmask_b32_e64 v77, v77, v93, s[48:49]
	v_add_f32_e32 v72, 1.0, v72
	v_rcp_f32_e32 v72, v72
	v_add_f32_e32 v75, v75, v77
	v_mul_f32_e32 v75, 0xbfb8aa3b, v75
	v_exp_f32_e32 v75, v75
	v_mul_f32_e32 v72, 0xc1000000, v72
	v_mul_f32_e32 v72, v73, v72
	v_sqrt_f32_e32 v62, v62
	v_mul_f32_e32 v72, 0x3fb8aa3b, v72
	v_sqrt_f32_e32 v54, v54
	v_exp_f32_e32 v73, v72
	v_add_f32_e32 v72, 1.0, v75
	v_pk_mul_f32 v[98:99], v[80:81], v[78:79]
	v_cndmask_b32_e64 v182, v165, v164, s[96:97]
	v_fma_f32 v64, -v65, v65, 1.0
	v_rcp_f32_e32 v75, v72
	v_pk_mul_f32 v[100:101], v[98:99], v[50:51]
	v_sqrt_f32_e32 v64, v64
	v_pk_fma_f32 v[78:79], v[98:99], v[50:51], v[100:101] op_sel_hi:[1,1,0]
	v_pk_mul_f32 v[90:91], v[182:183], v[180:181]
	v_mov_b32_e32 v83, v79
	v_pk_mul_f32 v[92:93], v[90:91], v[62:63]
	v_cndmask_b32_e64 v77, v167, v162, s[96:97]
	v_pk_mul_f32 v[102:103], v[82:83], v[54:55]
	v_pk_fma_f32 v[80:81], v[90:91], v[62:63], v[92:93] op_sel_hi:[1,1,0]
	v_mul_f32_e32 v190, v77, v75
	v_pk_fma_f32 v[78:79], v[82:83], v[54:55], v[102:103] op_sel_hi:[1,1,0]
	v_mov_b32_e32 v77, v81
	v_rcp_f32_e32 v84, v52
	v_fma_f32 v52, -v53, v53, 1.0
	v_mov_b32_e32 v89, v79
	v_pk_mul_f32 v[94:95], v[76:77], v[64:65]
	v_sqrt_f32_e32 v52, v52
	v_mul_f32_e32 v50, v173, v51
	v_pk_mul_f32 v[104:105], v[88:89], v[58:59]
	v_pk_fma_f32 v[76:77], v[76:77], v[64:65], v[94:95] op_sel_hi:[1,1,0]
	v_mul_f32_e32 v50, v55, v50
	v_pk_fma_f32 v[78:79], v[88:89], v[58:59], v[104:105] op_sel_hi:[1,1,0]
	v_mov_b32_e32 v179, v77
	v_cndmask_b32_e64 v86, v161, v160, s[96:97]
	v_fma_f32 v56, -v57, v57, 1.0
	v_mul_f32_e32 v78, v59, v50
	v_mul_f32_e32 v50, v175, v63
	v_pk_mul_f32 v[96:97], v[178:179], v[68:69]
	v_sqrt_f32_e32 v56, v56
	v_mul_f32_e32 v50, v65, v50
	v_pk_fma_f32 v[76:77], v[178:179], v[68:69], v[96:97] op_sel_hi:[1,1,0]
	v_pk_mul_f32 v[82:83], v[86:87], v[84:85]
	v_mul_f32_e32 v76, v69, v50
	v_pk_mul_f32 v[84:85], v[82:83], v[52:53]
	v_fma_f32 v60, -v61, v61, 1.0
	ds_write2_b64 v135, v[78:79], v[76:77] offset1:16
	v_pk_fma_f32 v[76:77], v[82:83], v[52:53], v[84:85] op_sel_hi:[1,1,0]
	v_sqrt_f32_e32 v60, v60
	v_mov_b32_e32 v107, v77
	v_rcp_f32_e32 v184, v66
	v_fma_f32 v66, -v67, v67, 1.0
	v_pk_mul_f32 v[86:87], v[106:107], v[56:57]
	v_sqrt_f32_e32 v66, v66
	v_pk_fma_f32 v[76:77], v[106:107], v[56:57], v[86:87] op_sel_hi:[1,1,0]
	v_cndmask_b32_e64 v186, v169, v168, s[96:97]
	v_mov_b32_e32 v75, v77
	v_fma_f32 v70, -v71, v71, 1.0
	v_pk_mul_f32 v[88:89], v[74:75], v[60:61]
	v_sqrt_f32_e32 v70, v70
	v_pk_fma_f32 v[106:107], v[74:75], v[60:61], v[88:89] op_sel_hi:[1,1,0]
	v_pk_mul_f32 v[74:75], v[186:187], v[184:185]
	v_fma_f32 v72, -v73, v73, 1.0
	v_pk_mul_f32 v[76:77], v[74:75], v[66:67]
	v_sqrt_f32_e32 v72, v72
	v_pk_fma_f32 v[78:79], v[74:75], v[66:67], v[76:77] op_sel_hi:[1,1,0]
	v_mul_f32_e32 v50, v174, v53
	v_mov_b32_e32 v189, v79
	v_pk_mul_f32 v[78:79], v[188:189], v[70:71]
	v_mul_f32_e32 v50, v57, v50
	v_pk_fma_f32 v[80:81], v[188:189], v[70:71], v[78:79] op_sel_hi:[1,1,0]
	v_mul_f32_e32 v106, v61, v50
	v_mov_b32_e32 v191, v81
	v_mul_f32_e32 v50, v176, v67
	v_pk_mul_f32 v[80:81], v[190:191], v[72:73]
	v_cndmask_b32_e64 v177, v113, v108, s[96:97]
	v_mul_f32_e32 v50, v71, v50
	v_pk_fma_f32 v[178:179], v[190:191], v[72:73], v[80:81] op_sel_hi:[1,1,0]
	v_mad_u32_u24 v52, v177, s54, v132
	v_mul_f32_e32 v178, v73, v50
	ds_write2_b64 v135, v[106:107], v[178:179] offset0:132 offset1:148
	s_waitcnt vmcnt(0)
	ds_write_b128 v133, v[210:213] offset:37440
	ds_write_b128 v134, v[214:217] offset:37440
	s_waitcnt lgkmcnt(0)
	s_barrier
	s_lshl_b32 s26, s7, 9
	s_or_b32 s68, s26, s33
	s_lshl_b64 s[26:27], s[68:69], 3
	s_add_u32 s28, s93, s26
	s_addc_u32 s29, s90, s27
	s_or_b32 s7, s7, s91
	s_lshl_b32 s7, s7, 9
	ds_read_b64 v[192:193], v52
	ds_read_b64 v[194:195], v52 offset:8
	ds_read_b64 v[196:197], v52 offset:16
	ds_read_b64 v[198:199], v52 offset:24
	s_waitcnt lgkmcnt(0)
	v_mov_b32_e32 v200, 1.0
	v_mov_b32_e32 v201, 0
	v_mov_b32_e32 v202, 1.0
	v_mov_b32_e32 v203, 0
	v_mov_b32_e32 v204, 1.0
	v_mov_b32_e32 v205, 0
	v_mov_b32_e32 v206, 1.0
	v_mov_b32_e32 v207, 0
	v_fmac_f32_dpp v193, v193, v192 row_shr:1 row_mask:0xf bank_mask:0xf
	v_fmac_f32_dpp v195, v195, v194 row_shr:1 row_mask:0xf bank_mask:0xf
	v_fmac_f32_dpp v197, v197, v196 row_shr:1 row_mask:0xf bank_mask:0xf
	v_fmac_f32_dpp v199, v199, v198 row_shr:1 row_mask:0xf bank_mask:0xf
	v_mul_f32_dpp v192, v192, v192 row_shr:1 row_mask:0xf bank_mask:0xf
	v_mul_f32_dpp v194, v194, v194 row_shr:1 row_mask:0xf bank_mask:0xf
	v_mul_f32_dpp v196, v196, v196 row_shr:1 row_mask:0xf bank_mask:0xf
	v_mul_f32_dpp v198, v198, v198 row_shr:1 row_mask:0xf bank_mask:0xf
	v_fmac_f32_dpp v193, v193, v192 row_shr:2 row_mask:0xf bank_mask:0xf
	v_fmac_f32_dpp v195, v195, v194 row_shr:2 row_mask:0xf bank_mask:0xf
	v_fmac_f32_dpp v197, v197, v196 row_shr:2 row_mask:0xf bank_mask:0xf
	v_fmac_f32_dpp v199, v199, v198 row_shr:2 row_mask:0xf bank_mask:0xf
	v_mul_f32_dpp v192, v192, v192 row_shr:2 row_mask:0xf bank_mask:0xf
	v_mul_f32_dpp v194, v194, v194 row_shr:2 row_mask:0xf bank_mask:0xf
	v_mul_f32_dpp v196, v196, v196 row_shr:2 row_mask:0xf bank_mask:0xf
	v_mul_f32_dpp v198, v198, v198 row_shr:2 row_mask:0xf bank_mask:0xf
	v_fmac_f32_dpp v193, v193, v192 row_shr:4 row_mask:0xf bank_mask:0xf
	v_fmac_f32_dpp v195, v195, v194 row_shr:4 row_mask:0xf bank_mask:0xf
	v_fmac_f32_dpp v197, v197, v196 row_shr:4 row_mask:0xf bank_mask:0xf
	v_fmac_f32_dpp v199, v199, v198 row_shr:4 row_mask:0xf bank_mask:0xf
	v_mul_f32_dpp v192, v192, v192 row_shr:4 row_mask:0xf bank_mask:0xf
	v_mul_f32_dpp v194, v194, v194 row_shr:4 row_mask:0xf bank_mask:0xf
	v_mul_f32_dpp v196, v196, v196 row_shr:4 row_mask:0xf bank_mask:0xf
	v_mul_f32_dpp v198, v198, v198 row_shr:4 row_mask:0xf bank_mask:0xf
	v_fmac_f32_dpp v193, v193, v192 row_shr:8 row_mask:0xf bank_mask:0xf
	v_fmac_f32_dpp v195, v195, v194 row_shr:8 row_mask:0xf bank_mask:0xf
	v_fmac_f32_dpp v197, v197, v196 row_shr:8 row_mask:0xf bank_mask:0xf
	v_fmac_f32_dpp v199, v199, v198 row_shr:8 row_mask:0xf bank_mask:0xf
	v_mul_f32_dpp v192, v192, v192 row_shr:8 row_mask:0xf bank_mask:0xf
	v_mul_f32_dpp v194, v194, v194 row_shr:8 row_mask:0xf bank_mask:0xf
	v_mul_f32_dpp v196, v196, v196 row_shr:8 row_mask:0xf bank_mask:0xf
	v_mul_f32_dpp v198, v198, v198 row_shr:8 row_mask:0xf bank_mask:0xf
	v_fmac_f32_dpp v193, v193, v192 row_bcast:15 row_mask:0xa bank_mask:0xf
	v_fmac_f32_dpp v195, v195, v194 row_bcast:15 row_mask:0xa bank_mask:0xf
	v_fmac_f32_dpp v197, v197, v196 row_bcast:15 row_mask:0xa bank_mask:0xf
	v_fmac_f32_dpp v199, v199, v198 row_bcast:15 row_mask:0xa bank_mask:0xf
	v_mul_f32_dpp v192, v192, v192 row_bcast:15 row_mask:0xa bank_mask:0xf
	v_mul_f32_dpp v194, v194, v194 row_bcast:15 row_mask:0xa bank_mask:0xf
	v_mul_f32_dpp v196, v196, v196 row_bcast:15 row_mask:0xa bank_mask:0xf
	v_mul_f32_dpp v198, v198, v198 row_bcast:15 row_mask:0xa bank_mask:0xf
	v_fmac_f32_dpp v193, v193, v192 row_bcast:31 row_mask:0xc bank_mask:0xf
	v_fmac_f32_dpp v195, v195, v194 row_bcast:31 row_mask:0xc bank_mask:0xf
	v_fmac_f32_dpp v197, v197, v196 row_bcast:31 row_mask:0xc bank_mask:0xf
	v_fmac_f32_dpp v199, v199, v198 row_bcast:31 row_mask:0xc bank_mask:0xf
	v_mul_f32_dpp v192, v192, v192 row_bcast:31 row_mask:0xc bank_mask:0xf
	v_mul_f32_dpp v194, v194, v194 row_bcast:31 row_mask:0xc bank_mask:0xf
	v_mul_f32_dpp v196, v196, v196 row_bcast:31 row_mask:0xc bank_mask:0xf
	v_mul_f32_dpp v198, v198, v198 row_bcast:31 row_mask:0xc bank_mask:0xf
	v_mov_b32_dpp v201, v193 wave_shr:1 row_mask:0xf bank_mask:0xf
	v_mov_b32_dpp v203, v195 wave_shr:1 row_mask:0xf bank_mask:0xf
	v_mov_b32_dpp v205, v197 wave_shr:1 row_mask:0xf bank_mask:0xf
	v_mov_b32_dpp v207, v199 wave_shr:1 row_mask:0xf bank_mask:0xf
	v_mov_b32_dpp v200, v192 wave_shr:1 row_mask:0xf bank_mask:0xf
	v_mov_b32_dpp v202, v194 wave_shr:1 row_mask:0xf bank_mask:0xf
	v_mov_b32_dpp v204, v196 wave_shr:1 row_mask:0xf bank_mask:0xf
	v_mov_b32_dpp v206, v198 wave_shr:1 row_mask:0xf bank_mask:0xf
	ds_write_b64 v52, v[200:201]
	ds_write_b64 v52, v[202:203] offset:8
	ds_write_b64 v52, v[204:205] offset:16
	ds_write_b64 v52, v[206:207] offset:24
	s_and_saveexec_b64 s[30:31], s[50:51]
	s_cbranch_execz .Lscan_done
	s_and_b64 vcc, exec, s[70:71]
	s_cbranch_vccz .Lscan_ctx
	v_lshl_add_u64 v[208:209], v[46:47], 3, s[28:29]
	flat_store_dwordx2 v[208:209], v[192:193] sc1
	v_lshl_add_u64 v[208:209], v[48:49], 3, s[28:29]
	flat_store_dwordx2 v[208:209], v[194:195] offset:8 sc1
	flat_store_dwordx2 v[208:209], v[196:197] offset:16 sc1
	flat_store_dwordx2 v[208:209], v[198:199] offset:24 sc1
	s_branch .Lscan_done
